# MLA: rescale threshold tested on the half-local row max; cross-half max only on rare/first-tile paths
# baseline (speedup 1.0000x reference)
; #define MFMA32(a, b, c) __builtin_amdgcn_mfma_f32_32x32x16_bf16((a), (b), (c), 0, 0, 0)
; DI float pl32_max(float v) { auto rr = __builtin_amdgcn_permlane32_swap(__float_as_uint(v), __float_as_uint(v), false, false); return fmaxf(__uint_as_float(rr[0]), __uint_as_float(rr[1])); }
; template <int OFF> DI s16x4 tr_read_o(unsigned addr) { s16x4 r; asm volatile("ds_read_b64_tr_b16 %0, %1 offset:%2" : "=&v"(r) : "v"(addr), "i"(OFF) : "memory"); return r; }
; DI float max_nn(float a, float b) { return __builtin_amdgcn_fmed3f(a, b, __builtin_inff()); }
; DI void mla_unit(const Params& p, char* lds, int seqbase, int S, int h, int qb) {
;     ...
;     const u16* kl = Kl + cur * 64 * KP + r32 * KP + 8 * hi;
;     f32x16 p0, p1;
;     { const bf16x8 k0 = *(const bf16x8*)(kl), k1 = *(const bf16x8*)(kl + 32 * KP);
;       p0 = MFMA32(k0, qf[0], negm); p1 = MFMA32(k1, qf[0], negm); }
; #pragma unroll
;     for (int d0 = 1; d0 < 6; ++d0) {
;       const bf16x8 k0 = *(const bf16x8*)(kl + d0 * 16), k1 = *(const bf16x8*)(kl + 32 * KP + d0 * 16);
;       p0 = MFMA32(k0, qf[d0], p0); p1 = MFMA32(k1, qf[d0], p1);
;     }
;     const unsigned tb = trb + cur * (64 * VP * 2);
;     constexpr int R8 = 8 * VP * 2;
;     const s16x4 a0 = tr_read_o<0>(tb), b0 = tr_read_o<R8>(tb), a1 = tr_read_o<2 * R8>(tb), b1 = tr_read_o<3 * R8>(tb);
;     const s16x4 a2 = tr_read_o<4 * R8>(tb), b2 = tr_read_o<5 * R8>(tb), a3 = tr_read_o<6 * R8>(tb), b3 = tr_read_o<7 * R8>(tb);
;     const s16x4 c0 = tr_read_o<64>(tb), d0_ = tr_read_o<R8 + 64>(tb), c1 = tr_read_o<2 * R8 + 64>(tb), d1 = tr_read_o<3 * R8 + 64>(tb);
;     const s16x4 c2 = tr_read_o<4 * R8 + 64>(tb), d2 = tr_read_o<5 * R8 + 64>(tb), c3 = tr_read_o<6 * R8 + 64>(tb), d3 = tr_read_o<7 * R8 + 64>(tb);
;     float pmax = max_nn(p0[0], p1[0]);
; #pragma unroll
;     for (int r = 1; r < 16; ++r) pmax = max_nn(pmax, max_nn(p0[r], p1[r]));
;     pmax = pl32_max(pmax);
;     if (kt == 0 || __any(pmax > 8.f)) {
;       const float delta = kt == 0 ? pmax : fmaxf(pmax, 0.f);
.LBB0_1081:
	s_mul_i32 s28, s36, 0x3400
	v_add_u32_e32 v0, s28, v181
	ds_read_b128 v[2:5], v0
	ds_read_b128 v[6:9], v0 offset:32
	s_mul_i32 s28, s36, 0x3000
	s_cmp_eq_u32 s46, 0
	s_cselect_b64 s[50:51], -1, 0
	s_waitcnt lgkmcnt(1)
	v_mfma_f32_32x32x16_bf16 v[64:79], v[2:5], v[116:119], v[48:63]
	ds_read_b128 v[2:5], v0 offset:6656
	ds_read_b128 v[10:13], v0 offset:6688
	s_cmp_lg_u32 s46, 0
	s_waitcnt lgkmcnt(1)
	v_mfma_f32_32x32x16_bf16 v[80:95], v[2:5], v[116:119], v[48:63]
	v_mfma_f32_32x32x16_bf16 v[64:79], v[6:9], v[120:123], v[64:79]
	ds_read_b128 v[2:5], v0 offset:64
	ds_read_b128 v[6:9], v0 offset:96
	s_waitcnt lgkmcnt(2)
	v_mfma_f32_32x32x16_bf16 v[80:95], v[10:13], v[120:123], v[80:95]
	s_waitcnt lgkmcnt(1)
	v_mfma_f32_32x32x16_bf16 v[64:79], v[2:5], v[124:127], v[64:79]
	ds_read_b128 v[2:5], v0 offset:6720
	ds_read_b128 v[10:13], v0 offset:6752
	s_waitcnt lgkmcnt(1)
	v_mfma_f32_32x32x16_bf16 v[80:95], v[2:5], v[124:127], v[80:95]
	ds_read_b128 v[2:5], v0 offset:128
	ds_read_b128 v[186:189], v0 offset:160
	v_mfma_f32_32x32x16_bf16 v[64:79], v[6:9], v[128:131], v[64:79]
	s_waitcnt lgkmcnt(2)
	v_mfma_f32_32x32x16_bf16 v[80:95], v[10:13], v[128:131], v[80:95]
	s_waitcnt lgkmcnt(1)
	v_mfma_f32_32x32x16_bf16 v[64:79], v[2:5], v[112:115], v[64:79]
	ds_read_b128 v[2:5], v0 offset:6784
	ds_read_b128 v[132:135], v0 offset:6816
	v_add_u32_e32 v0, s28, v182
	ds_read_b64_tr_b16 v[144:145], v0 offset:0
	ds_read_b64_tr_b16 v[146:147], v0 offset:0x600
	ds_read_b64_tr_b16 v[136:137], v0 offset:0xc00
	ds_read_b64_tr_b16 v[138:139], v0 offset:0x1200
	ds_read_b64_tr_b16 v[10:11], v0 offset:0x1800
	s_waitcnt lgkmcnt(1)
	v_mfma_f32_32x32x16_bf16 v[80:95], v[2:5], v[112:115], v[80:95]
	ds_read_b64_tr_b16 v[12:13], v0 offset:0x1e00
	ds_read_b64_tr_b16 v[6:7], v0 offset:0x2400
	ds_read_b64_tr_b16 v[8:9], v0 offset:0x2a00
	ds_read_b64_tr_b16 v[148:149], v0 offset:64
	ds_read_b64_tr_b16 v[150:151], v0 offset:0x640
	ds_read_b64_tr_b16 v[140:141], v0 offset:0xc40
	ds_read_b64_tr_b16 v[142:143], v0 offset:0x1240
	s_waitcnt lgkmcnt(0)
	v_mfma_f32_32x32x16_bf16 v[80:95], v[132:135], v[108:111], v[80:95]
	ds_read_b64_tr_b16 v[132:133], v0 offset:0x1840
	ds_read_b64_tr_b16 v[134:135], v0 offset:0x1e40
	ds_read_b64_tr_b16 v[2:3], v0 offset:0x2440
	ds_read_b64_tr_b16 v[4:5], v0 offset:0x2a40
	v_mfma_f32_32x32x16_bf16 v[64:79], v[186:189], v[108:111], v[64:79]
	s_nop 10
	v_max3_f32 v0, v80, v81, v82
	v_max3_f32 v14, v64, v65, v66
	v_max3_f32 v0, v0, v83, v84
	v_max3_f32 v14, v14, v67, v68
	v_max3_f32 v0, v0, v85, v86
	v_max3_f32 v14, v14, v69, v70
	v_max3_f32 v0, v0, v87, v88
	v_max3_f32 v14, v14, v71, v72
	v_max3_f32 v0, v0, v89, v90
	v_max3_f32 v14, v14, v73, v74
	v_max3_f32 v0, v0, v91, v92
	v_max3_f32 v14, v14, v75, v76
	v_max3_f32 v0, v0, v93, v94
	v_max3_f32 v14, v14, v77, v78
	v_max3_f32 v0, v0, v95, v79
	v_max_f32_e32 v14, v0, v14
	s_cbranch_scc0 .Lmla_k0_0
	v_cmp_lt_f32_e32 vcc, s60, v14
	s_mov_b64 s[54:55], 0
	s_mov_b64 s[52:53], 0
	s_cbranch_vccnz .Lmla_rare_0

; DI float pl32_max(float v) { auto rr = __builtin_amdgcn_permlane32_swap(__float_as_uint(v), __float_as_uint(v), false, false); return fmaxf(__uint_as_float(rr[0]), __uint_as_float(rr[1])); }
; DI void mla_unit(const Params& p, char* lds, int seqbase, int S, int h, int qb) {
;     ...
;     pmax = pl32_max(pmax);
;     if (kt == 0 || __any(pmax > 8.f)) {
;       const float delta = kt == 0 ? pmax : fmaxf(pmax, 0.f);
;       const float alpha = kt == 0 ? 1.f : __builtin_amdgcn_exp2f(-delta);
; #pragma unroll
;       for (int r = 0; r < 16; ++r) { negm[r] -= delta; p0[r] -= delta; p1[r] -= delta; o0[r] *= alpha; o1[r] *= alpha; }
;       l_run *= alpha;
.Lmla_k0_0:
	v_mov_b32_e32 v0, v14
	s_nop 1
	v_permlane32_swap_b32_e32 v0, v14
	v_max_f32_e32 v14, v0, v14
	s_branch .LBB0_1091
.Lmla_rare_0:
	v_mov_b32_e32 v0, v14
	s_nop 1
	v_permlane32_swap_b32_e32 v0, v14
	v_max_f32_e32 v14, v0, v14
	v_max_f32_e32 v0, v14, v14
	v_max_f32_e32 v0, 0, v0
	s_mov_b64 s[52:53], -1

; #define MFMA32(a, b, c) __builtin_amdgcn_mfma_f32_32x32x16_bf16((a), (b), (c), 0, 0, 0)
; DI float pl32_max(float v) { auto rr = __builtin_amdgcn_permlane32_swap(__float_as_uint(v), __float_as_uint(v), false, false); return fmaxf(__uint_as_float(rr[0]), __uint_as_float(rr[1])); }
; template <int OFF> DI s16x4 tr_read_o(unsigned addr) { s16x4 r; asm volatile("ds_read_b64_tr_b16 %0, %1 offset:%2" : "=&v"(r) : "v"(addr), "i"(OFF) : "memory"); return r; }
; DI float max_nn(float a, float b) { return __builtin_amdgcn_fmed3f(a, b, __builtin_inff()); }
; DI void mla_unit(const Params& p, char* lds, int seqbase, int S, int h, int qb) {
;     ...
;     const u16* kl = Kl + cur * 64 * KP + r32 * KP + 8 * hi;
;     f32x16 p0, p1;
;     { const bf16x8 k0 = *(const bf16x8*)(kl), k1 = *(const bf16x8*)(kl + 32 * KP);
;       p0 = MFMA32(k0, qf[0], negm); p1 = MFMA32(k1, qf[0], negm); }
; #pragma unroll
;     for (int d0 = 1; d0 < 6; ++d0) {
;       const bf16x8 k0 = *(const bf16x8*)(kl + d0 * 16), k1 = *(const bf16x8*)(kl + 32 * KP + d0 * 16);
;       p0 = MFMA32(k0, qf[d0], p0); p1 = MFMA32(k1, qf[d0], p1);
;     }
;     const unsigned tb = trb + cur * (64 * VP * 2);
;     constexpr int R8 = 8 * VP * 2;
;     const s16x4 a0 = tr_read_o<0>(tb), b0 = tr_read_o<R8>(tb), a1 = tr_read_o<2 * R8>(tb), b1 = tr_read_o<3 * R8>(tb);
;     const s16x4 a2 = tr_read_o<4 * R8>(tb), b2 = tr_read_o<5 * R8>(tb), a3 = tr_read_o<6 * R8>(tb), b3 = tr_read_o<7 * R8>(tb);
;     const s16x4 c0 = tr_read_o<64>(tb), d0_ = tr_read_o<R8 + 64>(tb), c1 = tr_read_o<2 * R8 + 64>(tb), d1 = tr_read_o<3 * R8 + 64>(tb);
;     const s16x4 c2 = tr_read_o<4 * R8 + 64>(tb), d2 = tr_read_o<5 * R8 + 64>(tb), c3 = tr_read_o<6 * R8 + 64>(tb), d3 = tr_read_o<7 * R8 + 64>(tb);
;     float pmax = max_nn(p0[0], p1[0]);
; #pragma unroll
;     for (int r = 1; r < 16; ++r) pmax = max_nn(pmax, max_nn(p0[r], p1[r]));
;     pmax = pl32_max(pmax);
;     if (kt == 0 || __any(pmax > 8.f)) {
;       const float delta = kt == 0 ? pmax : fmaxf(pmax, 0.f);
.LBB0_1111:
	s_mul_i32 s28, s18, 0x3400
	v_add_u32_e32 v2, s28, v181
	ds_read_b128 v[4:7], v2
	ds_read_b128 v[8:11], v2 offset:32
	s_mul_i32 s28, s18, 0x3000
	s_cmp_eq_u32 s38, 0
	s_cselect_b64 s[46:47], -1, 0
	s_waitcnt lgkmcnt(1)
	v_mfma_f32_32x32x16_bf16 v[66:81], v[4:7], v[118:121], v[50:65]
	ds_read_b128 v[4:7], v2 offset:6656
	ds_read_b128 v[12:15], v2 offset:6688
	s_cmp_lg_u32 s38, 0
	s_waitcnt lgkmcnt(1)
	v_mfma_f32_32x32x16_bf16 v[82:97], v[4:7], v[118:121], v[50:65]
	v_mfma_f32_32x32x16_bf16 v[66:81], v[8:11], v[122:125], v[66:81]
	ds_read_b128 v[4:7], v2 offset:64
	ds_read_b128 v[8:11], v2 offset:96
	s_waitcnt lgkmcnt(2)
	v_mfma_f32_32x32x16_bf16 v[82:97], v[12:15], v[122:125], v[82:97]
	s_waitcnt lgkmcnt(1)
	v_mfma_f32_32x32x16_bf16 v[66:81], v[4:7], v[126:129], v[66:81]
	ds_read_b128 v[4:7], v2 offset:6720
	ds_read_b128 v[12:15], v2 offset:6752
	s_waitcnt lgkmcnt(1)
	v_mfma_f32_32x32x16_bf16 v[82:97], v[4:7], v[126:129], v[82:97]
	ds_read_b128 v[4:7], v2 offset:128
	ds_read_b128 v[188:191], v2 offset:160
	v_mfma_f32_32x32x16_bf16 v[66:81], v[8:11], v[130:133], v[66:81]
	s_waitcnt lgkmcnt(2)
	v_mfma_f32_32x32x16_bf16 v[82:97], v[12:15], v[130:133], v[82:97]
	s_waitcnt lgkmcnt(1)
	v_mfma_f32_32x32x16_bf16 v[66:81], v[4:7], v[114:117], v[66:81]
	ds_read_b128 v[4:7], v2 offset:6784
	ds_read_b128 v[134:137], v2 offset:6816
	v_add_u32_e32 v2, s28, v182
	ds_read_b64_tr_b16 v[146:147], v2 offset:0
	ds_read_b64_tr_b16 v[148:149], v2 offset:0x600
	ds_read_b64_tr_b16 v[138:139], v2 offset:0xc00
	ds_read_b64_tr_b16 v[140:141], v2 offset:0x1200
	ds_read_b64_tr_b16 v[12:13], v2 offset:0x1800
	s_waitcnt lgkmcnt(1)
	v_mfma_f32_32x32x16_bf16 v[82:97], v[4:7], v[114:117], v[82:97]
	ds_read_b64_tr_b16 v[14:15], v2 offset:0x1e00
	ds_read_b64_tr_b16 v[8:9], v2 offset:0x2400
	ds_read_b64_tr_b16 v[10:11], v2 offset:0x2a00
	ds_read_b64_tr_b16 v[150:151], v2 offset:64
	ds_read_b64_tr_b16 v[152:153], v2 offset:0x640
	ds_read_b64_tr_b16 v[142:143], v2 offset:0xc40
	ds_read_b64_tr_b16 v[144:145], v2 offset:0x1240
	s_waitcnt lgkmcnt(0)
	v_mfma_f32_32x32x16_bf16 v[82:97], v[134:137], v[110:113], v[82:97]
	ds_read_b64_tr_b16 v[134:135], v2 offset:0x1840
	ds_read_b64_tr_b16 v[136:137], v2 offset:0x1e40
	ds_read_b64_tr_b16 v[4:5], v2 offset:0x2440
	ds_read_b64_tr_b16 v[6:7], v2 offset:0x2a40
	v_mfma_f32_32x32x16_bf16 v[66:81], v[188:191], v[110:113], v[66:81]
	s_nop 10
	v_max3_f32 v2, v82, v83, v84
	v_max3_f32 v16, v66, v67, v68
	v_max3_f32 v2, v2, v85, v86
	v_max3_f32 v16, v16, v69, v70
	v_max3_f32 v2, v2, v87, v88
	v_max3_f32 v16, v16, v71, v72
	v_max3_f32 v2, v2, v89, v90
	v_max3_f32 v16, v16, v73, v74
	v_max3_f32 v2, v2, v91, v92
	v_max3_f32 v16, v16, v75, v76
	v_max3_f32 v2, v2, v93, v94
	v_max3_f32 v16, v16, v77, v78
	v_max3_f32 v2, v2, v95, v96
	v_max3_f32 v16, v16, v79, v80
	v_max3_f32 v2, v2, v97, v81
	v_max_f32_e32 v16, v2, v16
	s_cbranch_scc0 .Lmla_k0_1
	v_cmp_lt_f32_e32 vcc, s21, v16
	s_mov_b64 s[50:51], 0
	s_mov_b64 s[48:49], 0
	s_cbranch_vccnz .Lmla_rare_1

; DI float pl32_max(float v) { auto rr = __builtin_amdgcn_permlane32_swap(__float_as_uint(v), __float_as_uint(v), false, false); return fmaxf(__uint_as_float(rr[0]), __uint_as_float(rr[1])); }
; DI void mla_unit(const Params& p, char* lds, int seqbase, int S, int h, int qb) {
;     ...
;     pmax = pl32_max(pmax);
;     if (kt == 0 || __any(pmax > 8.f)) {
;       const float delta = kt == 0 ? pmax : fmaxf(pmax, 0.f);
;       const float alpha = kt == 0 ? 1.f : __builtin_amdgcn_exp2f(-delta);
; #pragma unroll
;       for (int r = 0; r < 16; ++r) { negm[r] -= delta; p0[r] -= delta; p1[r] -= delta; o0[r] *= alpha; o1[r] *= alpha; }
;       l_run *= alpha;
.Lmla_k0_1:
	v_mov_b32_e32 v2, v16
	s_nop 1
	v_permlane32_swap_b32_e32 v2, v16
	v_max_f32_e32 v16, v2, v16
	s_branch .LBB0_1121
.Lmla_rare_1:
	v_mov_b32_e32 v2, v16
	s_nop 1
	v_permlane32_swap_b32_e32 v2, v16
	v_max_f32_e32 v16, v2, v16
	v_max_f32_e32 v2, v16, v16
	v_max_f32_e32 v2, 0, v2
	s_mov_b64 s[48:49], -1
